# v098 + P0 adaLN GEMV software-pipelined 4 deep (16 weight loads in flight), placement matched
# baseline (speedup 1.0000x reference)
; __global__ void __launch_bounds__(NT, 2) mk_fwd(Args args) {
;     ...
;             float* sct = (float*)lds;
;             for (int i = tid; i < 8 * 2048; i += NT) { const int b = i >> 11, k = i & 2047; const float cv = c[i]; sct[k * 8 + b] = cv / (1.0f + __expf(-cv)); }
;             __syncthreads();
;             const int n0 = bx * 64, rg = lane >> 4, cl = lane & 15;
;             f32x4 acc[8];
; #pragma unroll
;             for (int b = 0; b < 8; ++b) acc[b] = (f32x4){0.f, 0.f, 0.f, 0.f};
;             const float* wp = ada_w + (size_t)(wave * 256 + rg) * NMODC + n0 + cl * 4;
; #pragma unroll 4
;             for (int i = 0; i < 64; ++i) {
;                 const f32x4 w = *(const f32x4*)(wp + (size_t)i * 4 * NMODC);
.LBB0_20:
	global_load_dword v4, v[0:1], off
	v_add_u32_e32 v7, 0x200, v3
	v_lshrrev_b32_e32 v6, 9, v3
	v_cmp_lt_u32_e32 vcc, s3, v3
	v_mov_b32_e32 v3, v7
	v_and_b32_e32 v5, 0x3ff8, v2
	v_lshlrev_b32_e32 v5, 2, v5
	v_and_b32_e32 v6, 0x7ffffc, v6
	v_add3_u32 v5, 0, v5, v6
	s_or_b64 s[26:27], vcc, s[26:27]
	v_lshl_add_u64 v[0:1], v[0:1], 0, s[28:29]
	v_add_u32_e32 v2, 0x1000, v2
	s_waitcnt vmcnt(0)
	v_mul_f32_e32 v7, 0xbfb8aa3b, v4
	v_exp_f32_e32 v7, v7
	s_nop 0
	v_add_f32_e32 v6, 1.0, v7
	v_div_scale_f32 v7, s[30:31], v6, v6, v4
	v_rcp_f32_e32 v8, v7
	v_div_scale_f32 v9, vcc, v4, v6, v4
	v_fma_f32 v10, -v7, v8, 1.0
	v_fmac_f32_e32 v8, v10, v8
	v_mul_f32_e32 v10, v9, v8
	v_fma_f32 v11, -v7, v10, v9
	v_fmac_f32_e32 v10, v11, v8
	v_fma_f32 v7, -v7, v10, v9
	v_div_fmas_f32 v7, v7, v8, v10
	v_div_fixup_f32 v4, v7, v6, v4
	ds_write_b32 v5, v4
	s_andn2_b64 exec, exec, s[26:27]
	s_cbranch_execnz .LBB0_20
	s_or_b64 exec, exec, s[26:27]
	s_lshl_b32 s3, s85, 13
	v_lshrrev_b32_e32 v0, 4, v128
	s_add_i32 s3, s3, 0
	s_lshl_b32 s26, s2, 6
	v_lshl_add_u32 v43, v0, 5, s3
	v_lshl_or_b32 v0, s85, 8, v0
	s_mov_b32 s3, 0xc000
	s_ashr_i32 s27, s26, 31
	v_mad_i64_i32 v[0:1], s[28:29], v0, s3, 0
	s_lshl_b64 s[28:29], s[26:27], 2
	v_and_b32_e32 v2, 15, v168
	s_add_u32 s28, s40, s28
	v_lshl_or_b32 v0, v2, 4, v0
	s_addc_u32 s29, s41, s29
	v_mov_b32_e32 v38, 0
	v_lshl_add_u64 v[36:37], s[28:29], 0, v[0:1]
	s_mov_b64 s[28:29], 0
	s_mov_b32 s3, 0x30000
	s_mov_b32 s30, 0x60000
	s_mov_b32 s31, 0x90000
	v_mov_b32_e32 v39, v38
	v_mov_b32_e32 v40, v38
	v_mov_b32_e32 v41, v38
	v_mov_b32_e32 v34, v38
	v_mov_b32_e32 v35, v38
	v_mov_b32_e32 v32, v38
	v_mov_b32_e32 v33, v38
	v_mov_b32_e32 v30, v38
	v_mov_b32_e32 v31, v38
	v_mov_b32_e32 v28, v38
	v_mov_b32_e32 v29, v38
	v_mov_b32_e32 v26, v38
	v_mov_b32_e32 v27, v38
	v_mov_b32_e32 v24, v38
	v_mov_b32_e32 v25, v38
	v_mov_b32_e32 v22, v38
	v_mov_b32_e32 v23, v38
	v_mov_b32_e32 v20, v38
	v_mov_b32_e32 v21, v38
	v_mov_b32_e32 v18, v38
	v_mov_b32_e32 v19, v38
	v_mov_b32_e32 v16, v38
	v_mov_b32_e32 v17, v38
	v_mov_b32_e32 v14, v38
	v_mov_b32_e32 v15, v38
	v_mov_b32_e32 v12, v38
	v_mov_b32_e32 v13, v38
	v_mov_b32_e32 v10, v38
	v_mov_b32_e32 v11, v38
	v_mov_b32_e32 v8, v38
	v_mov_b32_e32 v9, v38
	s_waitcnt lgkmcnt(0)
	s_barrier
	v_lshl_add_u64 v[234:235], v[36:37], 0, s[28:29]
	v_add_co_u32_e32 v236, vcc, s3, v234
	s_nop 1
	v_addc_co_u32_e32 v237, vcc, 0, v235, vcc
	v_add_co_u32_e32 v238, vcc, s30, v234
	s_nop 1
	v_addc_co_u32_e32 v239, vcc, 0, v235, vcc
	v_add_co_u32_e32 v240, vcc, s31, v234
	s_nop 1
	v_addc_co_u32_e32 v241, vcc, 0, v235, vcc
	global_load_dwordx4 v[170:173], v[234:235], off
	global_load_dwordx4 v[174:177], v[236:237], off
	global_load_dwordx4 v[178:181], v[238:239], off
	global_load_dwordx4 v[182:185], v[240:241], off
	s_add_u32 s28, s28, 0xc0000
	s_sub_u32 s99, s28, 0xc00000
	s_cmp_ge_u32 s28, 0xc00000
	s_cselect_b32 s28, s99, s28
	v_lshl_add_u64 v[234:235], v[36:37], 0, s[28:29]
	v_add_co_u32_e32 v236, vcc, s3, v234
	s_nop 1
	v_addc_co_u32_e32 v237, vcc, 0, v235, vcc
	v_add_co_u32_e32 v238, vcc, s30, v234
	s_nop 1
	v_addc_co_u32_e32 v239, vcc, 0, v235, vcc
	v_add_co_u32_e32 v240, vcc, s31, v234
	s_nop 1
	v_addc_co_u32_e32 v241, vcc, 0, v235, vcc
	global_load_dwordx4 v[186:189], v[234:235], off
	global_load_dwordx4 v[190:193], v[236:237], off
	global_load_dwordx4 v[194:197], v[238:239], off
	global_load_dwordx4 v[198:201], v[240:241], off
	s_add_u32 s28, s28, 0xc0000
	s_sub_u32 s99, s28, 0xc00000
	s_cmp_ge_u32 s28, 0xc00000
	s_cselect_b32 s28, s99, s28
	v_lshl_add_u64 v[234:235], v[36:37], 0, s[28:29]
	v_add_co_u32_e32 v236, vcc, s3, v234
	s_nop 1
	v_addc_co_u32_e32 v237, vcc, 0, v235, vcc
	v_add_co_u32_e32 v238, vcc, s30, v234
	s_nop 1
	v_addc_co_u32_e32 v239, vcc, 0, v235, vcc
	v_add_co_u32_e32 v240, vcc, s31, v234
	s_nop 1
	v_addc_co_u32_e32 v241, vcc, 0, v235, vcc
	global_load_dwordx4 v[202:205], v[234:235], off
	global_load_dwordx4 v[206:209], v[236:237], off
	global_load_dwordx4 v[210:213], v[238:239], off
	global_load_dwordx4 v[214:217], v[240:241], off
	s_add_u32 s28, s28, 0xc0000
	s_sub_u32 s99, s28, 0xc00000
	s_cmp_ge_u32 s28, 0xc00000
	s_cselect_b32 s28, s99, s28
	v_lshl_add_u64 v[234:235], v[36:37], 0, s[28:29]
	v_add_co_u32_e32 v236, vcc, s3, v234
	s_nop 1
	v_addc_co_u32_e32 v237, vcc, 0, v235, vcc
	v_add_co_u32_e32 v238, vcc, s30, v234
	s_nop 1
	v_addc_co_u32_e32 v239, vcc, 0, v235, vcc
	v_add_co_u32_e32 v240, vcc, s31, v234
	s_nop 1
	v_addc_co_u32_e32 v241, vcc, 0, v235, vcc
	global_load_dwordx4 v[218:221], v[234:235], off
	global_load_dwordx4 v[222:225], v[236:237], off
	global_load_dwordx4 v[226:229], v[238:239], off
	global_load_dwordx4 v[230:233], v[240:241], off
	s_add_u32 s28, s28, 0xc0000
	s_sub_u32 s99, s28, 0xc00000
	s_cmp_ge_u32 s28, 0xc00000
	s_cselect_b32 s28, s99, s28
	s_mov_b32 s98, 0
; __global__ void __launch_bounds__(NT, 2) mk_fwd(Args args) {
;     ...
;             for (int i = 0; i < 64; ++i) {
;                 const f32x4 w = *(const f32x4*)(wp + (size_t)i * 4 * NMODC);
;                 const int k = wave * 256 + i * 4 + rg;
;                 const f32x4 s0 = *(const f32x4*)(sct + k * 8), s1 = *(const f32x4*)(sct + k * 8 + 4);
;                 acc[0] += w * s0.x; acc[1] += w * s0.y; acc[2] += w * s0.z; acc[3] += w * s0.w;
;                 acc[4] += w * s1.x; acc[5] += w * s1.y; acc[6] += w * s1.z; acc[7] += w * s1.w;
;             }
.Lgemv_loop:
	ds_read_b128 v[4:7], v43
	ds_read_b128 v[0:3], v43 offset:16
	ds_read_b128 v[44:47], v43 offset:128
	ds_read_b128 v[48:51], v43 offset:144
	s_waitcnt lgkmcnt(3)
	v_mov_b32_e32 v84, v7
	ds_read_b128 v[68:71], v43 offset:256
	ds_read_b128 v[72:75], v43 offset:272
	ds_read_b128 v[76:79], v43 offset:384
	ds_read_b128 v[80:83], v43 offset:400
	s_waitcnt lgkmcnt(6)
	v_mov_b32_e32 v86, v3
	s_waitcnt lgkmcnt(5)
	v_mov_b32_e32 v88, v47
	s_waitcnt lgkmcnt(4)
	v_mov_b32_e32 v90, v51
	s_waitcnt lgkmcnt(3)
	v_mov_b32_e32 v92, v71
	s_waitcnt lgkmcnt(2)
	v_mov_b32_e32 v94, v75
	s_waitcnt lgkmcnt(1)
	v_mov_b32_e32 v96, v79
	s_waitcnt lgkmcnt(0)
	v_mov_b32_e32 v98, v83
	v_add_u32_e32 v43, 0x200, v43
	s_waitcnt vmcnt(15)
	v_pk_fma_f32 v[40:41], v[172:173], v[4:5], v[40:41] op_sel_hi:[1,0,1]
	v_pk_fma_f32 v[38:39], v[170:171], v[4:5], v[38:39] op_sel_hi:[1,0,1]
	v_pk_fma_f32 v[32:33], v[172:173], v[4:5], v[32:33] op_sel:[0,1,0]
	v_pk_fma_f32 v[4:5], v[170:171], v[4:5], v[34:35] op_sel:[0,1,0]
	v_pk_fma_f32 v[30:31], v[170:171], v[6:7], v[30:31] op_sel_hi:[1,0,1]
	v_pk_fma_f32 v[6:7], v[172:173], v[6:7], v[28:29] op_sel_hi:[1,0,1]
	v_pk_fma_f32 v[20:21], v[172:173], v[0:1], v[20:21] op_sel_hi:[1,0,1]
	v_pk_fma_f32 v[22:23], v[170:171], v[0:1], v[22:23] op_sel_hi:[1,0,1]
	v_pk_fma_f32 v[16:17], v[172:173], v[0:1], v[16:17] op_sel:[0,1,0]
	v_pk_fma_f32 v[0:1], v[170:171], v[0:1], v[18:19] op_sel:[0,1,0]
	v_pk_fma_f32 v[14:15], v[170:171], v[2:3], v[14:15] op_sel_hi:[1,0,1]
	v_pk_fma_f32 v[2:3], v[172:173], v[2:3], v[12:13] op_sel_hi:[1,0,1]
	v_pk_fma_f32 v[12:13], v[170:171], v[84:85], v[26:27] op_sel_hi:[1,0,1]
	v_pk_fma_f32 v[18:19], v[172:173], v[84:85], v[24:25] op_sel_hi:[1,0,1]
	v_pk_fma_f32 v[10:11], v[170:171], v[86:87], v[10:11] op_sel_hi:[1,0,1]
	v_pk_fma_f32 v[8:9], v[172:173], v[86:87], v[8:9] op_sel_hi:[1,0,1]
	s_waitcnt vmcnt(14)
	v_pk_fma_f32 v[24:25], v[174:175], v[44:45], v[38:39] op_sel_hi:[1,0,1]
	v_pk_fma_f32 v[26:27], v[176:177], v[44:45], v[40:41] op_sel_hi:[1,0,1]
	v_pk_fma_f32 v[4:5], v[174:175], v[44:45], v[4:5] op_sel:[0,1,0]
	v_pk_fma_f32 v[28:29], v[176:177], v[44:45], v[32:33] op_sel:[0,1,0]
	v_pk_fma_f32 v[30:31], v[174:175], v[46:47], v[30:31] op_sel_hi:[1,0,1]
	v_pk_fma_f32 v[6:7], v[176:177], v[46:47], v[6:7] op_sel_hi:[1,0,1]
	v_pk_fma_f32 v[22:23], v[174:175], v[48:49], v[22:23] op_sel_hi:[1,0,1]
	v_pk_fma_f32 v[20:21], v[176:177], v[48:49], v[20:21] op_sel_hi:[1,0,1]
	v_pk_fma_f32 v[0:1], v[174:175], v[48:49], v[0:1] op_sel:[0,1,0]
	v_pk_fma_f32 v[16:17], v[176:177], v[48:49], v[16:17] op_sel:[0,1,0]
	v_pk_fma_f32 v[14:15], v[174:175], v[50:51], v[14:15] op_sel_hi:[1,0,1]
	v_pk_fma_f32 v[2:3], v[176:177], v[50:51], v[2:3] op_sel_hi:[1,0,1]
	v_pk_fma_f32 v[12:13], v[174:175], v[88:89], v[12:13] op_sel_hi:[1,0,1]
	v_pk_fma_f32 v[18:19], v[176:177], v[88:89], v[18:19] op_sel_hi:[1,0,1]
	v_pk_fma_f32 v[10:11], v[174:175], v[90:91], v[10:11] op_sel_hi:[1,0,1]
	v_pk_fma_f32 v[8:9], v[176:177], v[90:91], v[8:9] op_sel_hi:[1,0,1]
	s_waitcnt vmcnt(13)
	v_pk_fma_f32 v[26:27], v[180:181], v[68:69], v[26:27] op_sel_hi:[1,0,1]
	v_pk_fma_f32 v[24:25], v[178:179], v[68:69], v[24:25] op_sel_hi:[1,0,1]
	v_pk_fma_f32 v[28:29], v[180:181], v[68:69], v[28:29] op_sel:[0,1,0]
	v_pk_fma_f32 v[4:5], v[178:179], v[68:69], v[4:5] op_sel:[0,1,0]
	v_pk_fma_f32 v[6:7], v[180:181], v[70:71], v[6:7] op_sel_hi:[1,0,1]
	v_pk_fma_f32 v[30:31], v[178:179], v[70:71], v[30:31] op_sel_hi:[1,0,1]
	v_pk_fma_f32 v[20:21], v[180:181], v[72:73], v[20:21] op_sel_hi:[1,0,1]
	v_pk_fma_f32 v[22:23], v[178:179], v[72:73], v[22:23] op_sel_hi:[1,0,1]
	v_pk_fma_f32 v[16:17], v[180:181], v[72:73], v[16:17] op_sel:[0,1,0]
	v_pk_fma_f32 v[0:1], v[178:179], v[72:73], v[0:1] op_sel:[0,1,0]
	v_pk_fma_f32 v[2:3], v[180:181], v[74:75], v[2:3] op_sel_hi:[1,0,1]
	v_pk_fma_f32 v[14:15], v[178:179], v[74:75], v[14:15] op_sel_hi:[1,0,1]
	v_pk_fma_f32 v[18:19], v[180:181], v[92:93], v[18:19] op_sel_hi:[1,0,1]
	v_pk_fma_f32 v[12:13], v[178:179], v[92:93], v[12:13] op_sel_hi:[1,0,1]
	v_pk_fma_f32 v[8:9], v[180:181], v[94:95], v[8:9] op_sel_hi:[1,0,1]
	v_pk_fma_f32 v[10:11], v[178:179], v[94:95], v[10:11] op_sel_hi:[1,0,1]
	s_waitcnt vmcnt(12)
	v_pk_fma_f32 v[40:41], v[184:185], v[76:77], v[26:27] op_sel_hi:[1,0,1]
	v_pk_fma_f32 v[38:39], v[182:183], v[76:77], v[24:25] op_sel_hi:[1,0,1]
	v_pk_fma_f32 v[32:33], v[184:185], v[76:77], v[28:29] op_sel:[0,1,0]
	v_pk_fma_f32 v[34:35], v[182:183], v[76:77], v[4:5] op_sel:[0,1,0]
	v_pk_fma_f32 v[28:29], v[184:185], v[78:79], v[6:7] op_sel_hi:[1,0,1]
	v_pk_fma_f32 v[30:31], v[182:183], v[78:79], v[30:31] op_sel_hi:[1,0,1]
	v_pk_fma_f32 v[24:25], v[184:185], v[96:97], v[18:19] op_sel_hi:[1,0,1]
	v_pk_fma_f32 v[26:27], v[182:183], v[96:97], v[12:13] op_sel_hi:[1,0,1]
	v_pk_fma_f32 v[20:21], v[184:185], v[80:81], v[20:21] op_sel_hi:[1,0,1]
	v_pk_fma_f32 v[22:23], v[182:183], v[80:81], v[22:23] op_sel_hi:[1,0,1]
	v_pk_fma_f32 v[16:17], v[184:185], v[80:81], v[16:17] op_sel:[0,1,0]
	v_pk_fma_f32 v[18:19], v[182:183], v[80:81], v[0:1] op_sel:[0,1,0]
	v_pk_fma_f32 v[12:13], v[184:185], v[82:83], v[2:3] op_sel_hi:[1,0,1]
	v_pk_fma_f32 v[14:15], v[182:183], v[82:83], v[14:15] op_sel_hi:[1,0,1]
	v_pk_fma_f32 v[8:9], v[184:185], v[98:99], v[8:9] op_sel_hi:[1,0,1]
	v_pk_fma_f32 v[10:11], v[182:183], v[98:99], v[10:11] op_sel_hi:[1,0,1]
	v_lshl_add_u64 v[234:235], v[36:37], 0, s[28:29]
	v_add_co_u32_e32 v236, vcc, s3, v234
	s_nop 1
	v_addc_co_u32_e32 v237, vcc, 0, v235, vcc
	v_add_co_u32_e32 v238, vcc, s30, v234
	s_nop 1
	v_addc_co_u32_e32 v239, vcc, 0, v235, vcc
	v_add_co_u32_e32 v240, vcc, s31, v234
	s_nop 1
	v_addc_co_u32_e32 v241, vcc, 0, v235, vcc
	global_load_dwordx4 v[170:173], v[234:235], off
	global_load_dwordx4 v[174:177], v[236:237], off
	global_load_dwordx4 v[178:181], v[238:239], off
	global_load_dwordx4 v[182:185], v[240:241], off
	s_add_u32 s28, s28, 0xc0000
	s_sub_u32 s99, s28, 0xc00000
	s_cmp_ge_u32 s28, 0xc00000
	s_cselect_b32 s28, s99, s28
	ds_read_b128 v[4:7], v43
	ds_read_b128 v[0:3], v43 offset:16
	ds_read_b128 v[44:47], v43 offset:128
	ds_read_b128 v[48:51], v43 offset:144
	s_waitcnt lgkmcnt(3)
; __global__ void __launch_bounds__(NT, 2) mk_fwd(Args args) {
;     ...
;             for (int i = 0; i < 64; ++i) {
;                 const f32x4 w = *(const f32x4*)(wp + (size_t)i * 4 * NMODC);
;                 const int k = wave * 256 + i * 4 + rg;
;                 const f32x4 s0 = *(const f32x4*)(sct + k * 8), s1 = *(const f32x4*)(sct + k * 8 + 4);
;                 acc[0] += w * s0.x; acc[1] += w * s0.y; acc[2] += w * s0.z; acc[3] += w * s0.w;
;                 acc[4] += w * s1.x; acc[5] += w * s1.y; acc[6] += w * s1.z; acc[7] += w * s1.w;
;             }
	v_mov_b32_e32 v84, v7
	ds_read_b128 v[68:71], v43 offset:256
	ds_read_b128 v[72:75], v43 offset:272
	ds_read_b128 v[76:79], v43 offset:384
	ds_read_b128 v[80:83], v43 offset:400
	s_waitcnt lgkmcnt(6)
	v_mov_b32_e32 v86, v3
	s_waitcnt lgkmcnt(5)
	v_mov_b32_e32 v88, v47
	s_waitcnt lgkmcnt(4)
	v_mov_b32_e32 v90, v51
	s_waitcnt lgkmcnt(3)
	v_mov_b32_e32 v92, v71
	s_waitcnt lgkmcnt(2)
	v_mov_b32_e32 v94, v75
	s_waitcnt lgkmcnt(1)
	v_mov_b32_e32 v96, v79
	s_waitcnt lgkmcnt(0)
	v_mov_b32_e32 v98, v83
	v_add_u32_e32 v43, 0x200, v43
	s_waitcnt vmcnt(15)
	v_pk_fma_f32 v[40:41], v[188:189], v[4:5], v[40:41] op_sel_hi:[1,0,1]
	v_pk_fma_f32 v[38:39], v[186:187], v[4:5], v[38:39] op_sel_hi:[1,0,1]
	v_pk_fma_f32 v[32:33], v[188:189], v[4:5], v[32:33] op_sel:[0,1,0]
	v_pk_fma_f32 v[4:5], v[186:187], v[4:5], v[34:35] op_sel:[0,1,0]
	v_pk_fma_f32 v[30:31], v[186:187], v[6:7], v[30:31] op_sel_hi:[1,0,1]
	v_pk_fma_f32 v[6:7], v[188:189], v[6:7], v[28:29] op_sel_hi:[1,0,1]
	v_pk_fma_f32 v[20:21], v[188:189], v[0:1], v[20:21] op_sel_hi:[1,0,1]
	v_pk_fma_f32 v[22:23], v[186:187], v[0:1], v[22:23] op_sel_hi:[1,0,1]
	v_pk_fma_f32 v[16:17], v[188:189], v[0:1], v[16:17] op_sel:[0,1,0]
	v_pk_fma_f32 v[0:1], v[186:187], v[0:1], v[18:19] op_sel:[0,1,0]
	v_pk_fma_f32 v[14:15], v[186:187], v[2:3], v[14:15] op_sel_hi:[1,0,1]
	v_pk_fma_f32 v[2:3], v[188:189], v[2:3], v[12:13] op_sel_hi:[1,0,1]
	v_pk_fma_f32 v[12:13], v[186:187], v[84:85], v[26:27] op_sel_hi:[1,0,1]
	v_pk_fma_f32 v[18:19], v[188:189], v[84:85], v[24:25] op_sel_hi:[1,0,1]
	v_pk_fma_f32 v[10:11], v[186:187], v[86:87], v[10:11] op_sel_hi:[1,0,1]
	v_pk_fma_f32 v[8:9], v[188:189], v[86:87], v[8:9] op_sel_hi:[1,0,1]
	s_waitcnt vmcnt(14)
	v_pk_fma_f32 v[24:25], v[190:191], v[44:45], v[38:39] op_sel_hi:[1,0,1]
	v_pk_fma_f32 v[26:27], v[192:193], v[44:45], v[40:41] op_sel_hi:[1,0,1]
	v_pk_fma_f32 v[4:5], v[190:191], v[44:45], v[4:5] op_sel:[0,1,0]
	v_pk_fma_f32 v[28:29], v[192:193], v[44:45], v[32:33] op_sel:[0,1,0]
	v_pk_fma_f32 v[30:31], v[190:191], v[46:47], v[30:31] op_sel_hi:[1,0,1]
	v_pk_fma_f32 v[6:7], v[192:193], v[46:47], v[6:7] op_sel_hi:[1,0,1]
	v_pk_fma_f32 v[22:23], v[190:191], v[48:49], v[22:23] op_sel_hi:[1,0,1]
	v_pk_fma_f32 v[20:21], v[192:193], v[48:49], v[20:21] op_sel_hi:[1,0,1]
	v_pk_fma_f32 v[0:1], v[190:191], v[48:49], v[0:1] op_sel:[0,1,0]
	v_pk_fma_f32 v[16:17], v[192:193], v[48:49], v[16:17] op_sel:[0,1,0]
	v_pk_fma_f32 v[14:15], v[190:191], v[50:51], v[14:15] op_sel_hi:[1,0,1]
	v_pk_fma_f32 v[2:3], v[192:193], v[50:51], v[2:3] op_sel_hi:[1,0,1]
	v_pk_fma_f32 v[12:13], v[190:191], v[88:89], v[12:13] op_sel_hi:[1,0,1]
	v_pk_fma_f32 v[18:19], v[192:193], v[88:89], v[18:19] op_sel_hi:[1,0,1]
	v_pk_fma_f32 v[10:11], v[190:191], v[90:91], v[10:11] op_sel_hi:[1,0,1]
	v_pk_fma_f32 v[8:9], v[192:193], v[90:91], v[8:9] op_sel_hi:[1,0,1]
	s_waitcnt vmcnt(13)
	v_pk_fma_f32 v[26:27], v[196:197], v[68:69], v[26:27] op_sel_hi:[1,0,1]
	v_pk_fma_f32 v[24:25], v[194:195], v[68:69], v[24:25] op_sel_hi:[1,0,1]
	v_pk_fma_f32 v[28:29], v[196:197], v[68:69], v[28:29] op_sel:[0,1,0]
	v_pk_fma_f32 v[4:5], v[194:195], v[68:69], v[4:5] op_sel:[0,1,0]
	v_pk_fma_f32 v[6:7], v[196:197], v[70:71], v[6:7] op_sel_hi:[1,0,1]
	v_pk_fma_f32 v[30:31], v[194:195], v[70:71], v[30:31] op_sel_hi:[1,0,1]
	v_pk_fma_f32 v[20:21], v[196:197], v[72:73], v[20:21] op_sel_hi:[1,0,1]
	v_pk_fma_f32 v[22:23], v[194:195], v[72:73], v[22:23] op_sel_hi:[1,0,1]
	v_pk_fma_f32 v[16:17], v[196:197], v[72:73], v[16:17] op_sel:[0,1,0]
	v_pk_fma_f32 v[0:1], v[194:195], v[72:73], v[0:1] op_sel:[0,1,0]
	v_pk_fma_f32 v[2:3], v[196:197], v[74:75], v[2:3] op_sel_hi:[1,0,1]
	v_pk_fma_f32 v[14:15], v[194:195], v[74:75], v[14:15] op_sel_hi:[1,0,1]
	v_pk_fma_f32 v[18:19], v[196:197], v[92:93], v[18:19] op_sel_hi:[1,0,1]
	v_pk_fma_f32 v[12:13], v[194:195], v[92:93], v[12:13] op_sel_hi:[1,0,1]
	v_pk_fma_f32 v[8:9], v[196:197], v[94:95], v[8:9] op_sel_hi:[1,0,1]
	v_pk_fma_f32 v[10:11], v[194:195], v[94:95], v[10:11] op_sel_hi:[1,0,1]
	s_waitcnt vmcnt(12)
	v_pk_fma_f32 v[40:41], v[200:201], v[76:77], v[26:27] op_sel_hi:[1,0,1]
	v_pk_fma_f32 v[38:39], v[198:199], v[76:77], v[24:25] op_sel_hi:[1,0,1]
	v_pk_fma_f32 v[32:33], v[200:201], v[76:77], v[28:29] op_sel:[0,1,0]
	v_pk_fma_f32 v[34:35], v[198:199], v[76:77], v[4:5] op_sel:[0,1,0]
	v_pk_fma_f32 v[28:29], v[200:201], v[78:79], v[6:7] op_sel_hi:[1,0,1]
	v_pk_fma_f32 v[30:31], v[198:199], v[78:79], v[30:31] op_sel_hi:[1,0,1]
	v_pk_fma_f32 v[24:25], v[200:201], v[96:97], v[18:19] op_sel_hi:[1,0,1]
	v_pk_fma_f32 v[26:27], v[198:199], v[96:97], v[12:13] op_sel_hi:[1,0,1]
	v_pk_fma_f32 v[20:21], v[200:201], v[80:81], v[20:21] op_sel_hi:[1,0,1]
	v_pk_fma_f32 v[22:23], v[198:199], v[80:81], v[22:23] op_sel_hi:[1,0,1]
	v_pk_fma_f32 v[16:17], v[200:201], v[80:81], v[16:17] op_sel:[0,1,0]
	v_pk_fma_f32 v[18:19], v[198:199], v[80:81], v[0:1] op_sel:[0,1,0]
	v_pk_fma_f32 v[12:13], v[200:201], v[82:83], v[2:3] op_sel_hi:[1,0,1]
	v_pk_fma_f32 v[14:15], v[198:199], v[82:83], v[14:15] op_sel_hi:[1,0,1]
	v_pk_fma_f32 v[8:9], v[200:201], v[98:99], v[8:9] op_sel_hi:[1,0,1]
	v_pk_fma_f32 v[10:11], v[198:199], v[98:99], v[10:11] op_sel_hi:[1,0,1]
	v_lshl_add_u64 v[234:235], v[36:37], 0, s[28:29]
	v_add_co_u32_e32 v236, vcc, s3, v234
	s_nop 1
	v_addc_co_u32_e32 v237, vcc, 0, v235, vcc
	v_add_co_u32_e32 v238, vcc, s30, v234
	s_nop 1
	v_addc_co_u32_e32 v239, vcc, 0, v235, vcc
	v_add_co_u32_e32 v240, vcc, s31, v234
	s_nop 1
	v_addc_co_u32_e32 v241, vcc, 0, v235, vcc
	global_load_dwordx4 v[186:189], v[234:235], off
	global_load_dwordx4 v[190:193], v[236:237], off
	global_load_dwordx4 v[194:197], v[238:239], off
	global_load_dwordx4 v[198:201], v[240:241], off
	s_add_u32 s28, s28, 0xc0000
	s_sub_u32 s99, s28, 0xc00000
	s_cmp_ge_u32 s28, 0xc00000
	s_cselect_b32 s28, s99, s28
	ds_read_b128 v[4:7], v43
	ds_read_b128 v[0:3], v43 offset:16
	ds_read_b128 v[44:47], v43 offset:128
	ds_read_b128 v[48:51], v43 offset:144
	s_waitcnt lgkmcnt(3)
; __global__ void __launch_bounds__(NT, 2) mk_fwd(Args args) {
;     ...
;             for (int i = 0; i < 64; ++i) {
;                 const f32x4 w = *(const f32x4*)(wp + (size_t)i * 4 * NMODC);
;                 const int k = wave * 256 + i * 4 + rg;
;                 const f32x4 s0 = *(const f32x4*)(sct + k * 8), s1 = *(const f32x4*)(sct + k * 8 + 4);
;                 acc[0] += w * s0.x; acc[1] += w * s0.y; acc[2] += w * s0.z; acc[3] += w * s0.w;
;                 acc[4] += w * s1.x; acc[5] += w * s1.y; acc[6] += w * s1.z; acc[7] += w * s1.w;
;             }
	v_mov_b32_e32 v84, v7
	ds_read_b128 v[68:71], v43 offset:256
	ds_read_b128 v[72:75], v43 offset:272
	ds_read_b128 v[76:79], v43 offset:384
	ds_read_b128 v[80:83], v43 offset:400
	s_waitcnt lgkmcnt(6)
	v_mov_b32_e32 v86, v3
	s_waitcnt lgkmcnt(5)
	v_mov_b32_e32 v88, v47
	s_waitcnt lgkmcnt(4)
	v_mov_b32_e32 v90, v51
	s_waitcnt lgkmcnt(3)
	v_mov_b32_e32 v92, v71
	s_waitcnt lgkmcnt(2)
	v_mov_b32_e32 v94, v75
	s_waitcnt lgkmcnt(1)
	v_mov_b32_e32 v96, v79
	s_waitcnt lgkmcnt(0)
	v_mov_b32_e32 v98, v83
	v_add_u32_e32 v43, 0x200, v43
	s_waitcnt vmcnt(15)
	v_pk_fma_f32 v[40:41], v[204:205], v[4:5], v[40:41] op_sel_hi:[1,0,1]
	v_pk_fma_f32 v[38:39], v[202:203], v[4:5], v[38:39] op_sel_hi:[1,0,1]
	v_pk_fma_f32 v[32:33], v[204:205], v[4:5], v[32:33] op_sel:[0,1,0]
	v_pk_fma_f32 v[4:5], v[202:203], v[4:5], v[34:35] op_sel:[0,1,0]
	v_pk_fma_f32 v[30:31], v[202:203], v[6:7], v[30:31] op_sel_hi:[1,0,1]
	v_pk_fma_f32 v[6:7], v[204:205], v[6:7], v[28:29] op_sel_hi:[1,0,1]
	v_pk_fma_f32 v[20:21], v[204:205], v[0:1], v[20:21] op_sel_hi:[1,0,1]
	v_pk_fma_f32 v[22:23], v[202:203], v[0:1], v[22:23] op_sel_hi:[1,0,1]
	v_pk_fma_f32 v[16:17], v[204:205], v[0:1], v[16:17] op_sel:[0,1,0]
	v_pk_fma_f32 v[0:1], v[202:203], v[0:1], v[18:19] op_sel:[0,1,0]
	v_pk_fma_f32 v[14:15], v[202:203], v[2:3], v[14:15] op_sel_hi:[1,0,1]
	v_pk_fma_f32 v[2:3], v[204:205], v[2:3], v[12:13] op_sel_hi:[1,0,1]
	v_pk_fma_f32 v[12:13], v[202:203], v[84:85], v[26:27] op_sel_hi:[1,0,1]
	v_pk_fma_f32 v[18:19], v[204:205], v[84:85], v[24:25] op_sel_hi:[1,0,1]
	v_pk_fma_f32 v[10:11], v[202:203], v[86:87], v[10:11] op_sel_hi:[1,0,1]
	v_pk_fma_f32 v[8:9], v[204:205], v[86:87], v[8:9] op_sel_hi:[1,0,1]
	s_waitcnt vmcnt(14)
	v_pk_fma_f32 v[24:25], v[206:207], v[44:45], v[38:39] op_sel_hi:[1,0,1]
	v_pk_fma_f32 v[26:27], v[208:209], v[44:45], v[40:41] op_sel_hi:[1,0,1]
	v_pk_fma_f32 v[4:5], v[206:207], v[44:45], v[4:5] op_sel:[0,1,0]
	v_pk_fma_f32 v[28:29], v[208:209], v[44:45], v[32:33] op_sel:[0,1,0]
	v_pk_fma_f32 v[30:31], v[206:207], v[46:47], v[30:31] op_sel_hi:[1,0,1]
	v_pk_fma_f32 v[6:7], v[208:209], v[46:47], v[6:7] op_sel_hi:[1,0,1]
	v_pk_fma_f32 v[22:23], v[206:207], v[48:49], v[22:23] op_sel_hi:[1,0,1]
	v_pk_fma_f32 v[20:21], v[208:209], v[48:49], v[20:21] op_sel_hi:[1,0,1]
	v_pk_fma_f32 v[0:1], v[206:207], v[48:49], v[0:1] op_sel:[0,1,0]
	v_pk_fma_f32 v[16:17], v[208:209], v[48:49], v[16:17] op_sel:[0,1,0]
	v_pk_fma_f32 v[14:15], v[206:207], v[50:51], v[14:15] op_sel_hi:[1,0,1]
	v_pk_fma_f32 v[2:3], v[208:209], v[50:51], v[2:3] op_sel_hi:[1,0,1]
	v_pk_fma_f32 v[12:13], v[206:207], v[88:89], v[12:13] op_sel_hi:[1,0,1]
	v_pk_fma_f32 v[18:19], v[208:209], v[88:89], v[18:19] op_sel_hi:[1,0,1]
	v_pk_fma_f32 v[10:11], v[206:207], v[90:91], v[10:11] op_sel_hi:[1,0,1]
	v_pk_fma_f32 v[8:9], v[208:209], v[90:91], v[8:9] op_sel_hi:[1,0,1]
	s_waitcnt vmcnt(13)
	v_pk_fma_f32 v[26:27], v[212:213], v[68:69], v[26:27] op_sel_hi:[1,0,1]
	v_pk_fma_f32 v[24:25], v[210:211], v[68:69], v[24:25] op_sel_hi:[1,0,1]
	v_pk_fma_f32 v[28:29], v[212:213], v[68:69], v[28:29] op_sel:[0,1,0]
	v_pk_fma_f32 v[4:5], v[210:211], v[68:69], v[4:5] op_sel:[0,1,0]
	v_pk_fma_f32 v[6:7], v[212:213], v[70:71], v[6:7] op_sel_hi:[1,0,1]
	v_pk_fma_f32 v[30:31], v[210:211], v[70:71], v[30:31] op_sel_hi:[1,0,1]
	v_pk_fma_f32 v[20:21], v[212:213], v[72:73], v[20:21] op_sel_hi:[1,0,1]
	v_pk_fma_f32 v[22:23], v[210:211], v[72:73], v[22:23] op_sel_hi:[1,0,1]
	v_pk_fma_f32 v[16:17], v[212:213], v[72:73], v[16:17] op_sel:[0,1,0]
	v_pk_fma_f32 v[0:1], v[210:211], v[72:73], v[0:1] op_sel:[0,1,0]
	v_pk_fma_f32 v[2:3], v[212:213], v[74:75], v[2:3] op_sel_hi:[1,0,1]
	v_pk_fma_f32 v[14:15], v[210:211], v[74:75], v[14:15] op_sel_hi:[1,0,1]
	v_pk_fma_f32 v[18:19], v[212:213], v[92:93], v[18:19] op_sel_hi:[1,0,1]
	v_pk_fma_f32 v[12:13], v[210:211], v[92:93], v[12:13] op_sel_hi:[1,0,1]
	v_pk_fma_f32 v[8:9], v[212:213], v[94:95], v[8:9] op_sel_hi:[1,0,1]
	v_pk_fma_f32 v[10:11], v[210:211], v[94:95], v[10:11] op_sel_hi:[1,0,1]
	s_waitcnt vmcnt(12)
	v_pk_fma_f32 v[40:41], v[216:217], v[76:77], v[26:27] op_sel_hi:[1,0,1]
	v_pk_fma_f32 v[38:39], v[214:215], v[76:77], v[24:25] op_sel_hi:[1,0,1]
	v_pk_fma_f32 v[32:33], v[216:217], v[76:77], v[28:29] op_sel:[0,1,0]
	v_pk_fma_f32 v[34:35], v[214:215], v[76:77], v[4:5] op_sel:[0,1,0]
	v_pk_fma_f32 v[28:29], v[216:217], v[78:79], v[6:7] op_sel_hi:[1,0,1]
	v_pk_fma_f32 v[30:31], v[214:215], v[78:79], v[30:31] op_sel_hi:[1,0,1]
	v_pk_fma_f32 v[24:25], v[216:217], v[96:97], v[18:19] op_sel_hi:[1,0,1]
	v_pk_fma_f32 v[26:27], v[214:215], v[96:97], v[12:13] op_sel_hi:[1,0,1]
	v_pk_fma_f32 v[20:21], v[216:217], v[80:81], v[20:21] op_sel_hi:[1,0,1]
	v_pk_fma_f32 v[22:23], v[214:215], v[80:81], v[22:23] op_sel_hi:[1,0,1]
	v_pk_fma_f32 v[16:17], v[216:217], v[80:81], v[16:17] op_sel:[0,1,0]
	v_pk_fma_f32 v[18:19], v[214:215], v[80:81], v[0:1] op_sel:[0,1,0]
	v_pk_fma_f32 v[12:13], v[216:217], v[82:83], v[2:3] op_sel_hi:[1,0,1]
	v_pk_fma_f32 v[14:15], v[214:215], v[82:83], v[14:15] op_sel_hi:[1,0,1]
	v_pk_fma_f32 v[8:9], v[216:217], v[98:99], v[8:9] op_sel_hi:[1,0,1]
	v_pk_fma_f32 v[10:11], v[214:215], v[98:99], v[10:11] op_sel_hi:[1,0,1]
	v_lshl_add_u64 v[234:235], v[36:37], 0, s[28:29]
	v_add_co_u32_e32 v236, vcc, s3, v234
	s_nop 1
	v_addc_co_u32_e32 v237, vcc, 0, v235, vcc
	v_add_co_u32_e32 v238, vcc, s30, v234
	s_nop 1
	v_addc_co_u32_e32 v239, vcc, 0, v235, vcc
	v_add_co_u32_e32 v240, vcc, s31, v234
	s_nop 1
	v_addc_co_u32_e32 v241, vcc, 0, v235, vcc
	global_load_dwordx4 v[202:205], v[234:235], off
	global_load_dwordx4 v[206:209], v[236:237], off
	global_load_dwordx4 v[210:213], v[238:239], off
	global_load_dwordx4 v[214:217], v[240:241], off
	s_add_u32 s28, s28, 0xc0000
	s_sub_u32 s99, s28, 0xc00000
	s_cmp_ge_u32 s28, 0xc00000
	s_cselect_b32 s28, s99, s28
	ds_read_b128 v[4:7], v43
	ds_read_b128 v[0:3], v43 offset:16
	ds_read_b128 v[44:47], v43 offset:128
	ds_read_b128 v[48:51], v43 offset:144
	s_waitcnt lgkmcnt(3)
; __global__ void __launch_bounds__(NT, 2) mk_fwd(Args args) {
;     ...
;             for (int i = 0; i < 64; ++i) {
;                 const f32x4 w = *(const f32x4*)(wp + (size_t)i * 4 * NMODC);
;                 const int k = wave * 256 + i * 4 + rg;
;                 const f32x4 s0 = *(const f32x4*)(sct + k * 8), s1 = *(const f32x4*)(sct + k * 8 + 4);
;                 acc[0] += w * s0.x; acc[1] += w * s0.y; acc[2] += w * s0.z; acc[3] += w * s0.w;
;                 acc[4] += w * s1.x; acc[5] += w * s1.y; acc[6] += w * s1.z; acc[7] += w * s1.w;
;             }
;             float* red = (float*)(lds + 65536);
; #pragma unroll
;             for (int b = 0; b < 8; ++b) {
; #pragma unroll
;                 for (int q = 0; q < 4; ++q) { float v = acc[b][q]; v += __shfl_xor(v, 16); v += __shfl_xor(v, 32); acc[b][q] = v; }
;                 if (rg == 0) *(f32x4*)(red + (wave * 8 + b) * 64 + cl * 4) = acc[b];
	v_mov_b32_e32 v84, v7
	ds_read_b128 v[68:71], v43 offset:256
	ds_read_b128 v[72:75], v43 offset:272
	ds_read_b128 v[76:79], v43 offset:384
	ds_read_b128 v[80:83], v43 offset:400
	s_waitcnt lgkmcnt(6)
	v_mov_b32_e32 v86, v3
	s_waitcnt lgkmcnt(5)
	v_mov_b32_e32 v88, v47
	s_waitcnt lgkmcnt(4)
	v_mov_b32_e32 v90, v51
	s_waitcnt lgkmcnt(3)
	v_mov_b32_e32 v92, v71
	s_waitcnt lgkmcnt(2)
	v_mov_b32_e32 v94, v75
	s_waitcnt lgkmcnt(1)
	v_mov_b32_e32 v96, v79
	s_waitcnt lgkmcnt(0)
	v_mov_b32_e32 v98, v83
	v_add_u32_e32 v43, 0x200, v43
	s_waitcnt vmcnt(15)
	v_pk_fma_f32 v[40:41], v[220:221], v[4:5], v[40:41] op_sel_hi:[1,0,1]
	v_pk_fma_f32 v[38:39], v[218:219], v[4:5], v[38:39] op_sel_hi:[1,0,1]
	v_pk_fma_f32 v[32:33], v[220:221], v[4:5], v[32:33] op_sel:[0,1,0]
	v_pk_fma_f32 v[4:5], v[218:219], v[4:5], v[34:35] op_sel:[0,1,0]
	v_pk_fma_f32 v[30:31], v[218:219], v[6:7], v[30:31] op_sel_hi:[1,0,1]
	v_pk_fma_f32 v[6:7], v[220:221], v[6:7], v[28:29] op_sel_hi:[1,0,1]
	v_pk_fma_f32 v[20:21], v[220:221], v[0:1], v[20:21] op_sel_hi:[1,0,1]
	v_pk_fma_f32 v[22:23], v[218:219], v[0:1], v[22:23] op_sel_hi:[1,0,1]
	v_pk_fma_f32 v[16:17], v[220:221], v[0:1], v[16:17] op_sel:[0,1,0]
	v_pk_fma_f32 v[0:1], v[218:219], v[0:1], v[18:19] op_sel:[0,1,0]
	v_pk_fma_f32 v[14:15], v[218:219], v[2:3], v[14:15] op_sel_hi:[1,0,1]
	v_pk_fma_f32 v[2:3], v[220:221], v[2:3], v[12:13] op_sel_hi:[1,0,1]
	v_pk_fma_f32 v[12:13], v[218:219], v[84:85], v[26:27] op_sel_hi:[1,0,1]
	v_pk_fma_f32 v[18:19], v[220:221], v[84:85], v[24:25] op_sel_hi:[1,0,1]
	v_pk_fma_f32 v[10:11], v[218:219], v[86:87], v[10:11] op_sel_hi:[1,0,1]
	v_pk_fma_f32 v[8:9], v[220:221], v[86:87], v[8:9] op_sel_hi:[1,0,1]
	s_waitcnt vmcnt(14)
	v_pk_fma_f32 v[24:25], v[222:223], v[44:45], v[38:39] op_sel_hi:[1,0,1]
	v_pk_fma_f32 v[26:27], v[224:225], v[44:45], v[40:41] op_sel_hi:[1,0,1]
	v_pk_fma_f32 v[4:5], v[222:223], v[44:45], v[4:5] op_sel:[0,1,0]
	v_pk_fma_f32 v[28:29], v[224:225], v[44:45], v[32:33] op_sel:[0,1,0]
	v_pk_fma_f32 v[30:31], v[222:223], v[46:47], v[30:31] op_sel_hi:[1,0,1]
	v_pk_fma_f32 v[6:7], v[224:225], v[46:47], v[6:7] op_sel_hi:[1,0,1]
	v_pk_fma_f32 v[22:23], v[222:223], v[48:49], v[22:23] op_sel_hi:[1,0,1]
	v_pk_fma_f32 v[20:21], v[224:225], v[48:49], v[20:21] op_sel_hi:[1,0,1]
	v_pk_fma_f32 v[0:1], v[222:223], v[48:49], v[0:1] op_sel:[0,1,0]
	v_pk_fma_f32 v[16:17], v[224:225], v[48:49], v[16:17] op_sel:[0,1,0]
	v_pk_fma_f32 v[14:15], v[222:223], v[50:51], v[14:15] op_sel_hi:[1,0,1]
	v_pk_fma_f32 v[2:3], v[224:225], v[50:51], v[2:3] op_sel_hi:[1,0,1]
	v_pk_fma_f32 v[12:13], v[222:223], v[88:89], v[12:13] op_sel_hi:[1,0,1]
	v_pk_fma_f32 v[18:19], v[224:225], v[88:89], v[18:19] op_sel_hi:[1,0,1]
	v_pk_fma_f32 v[10:11], v[222:223], v[90:91], v[10:11] op_sel_hi:[1,0,1]
	v_pk_fma_f32 v[8:9], v[224:225], v[90:91], v[8:9] op_sel_hi:[1,0,1]
	s_waitcnt vmcnt(13)
	v_pk_fma_f32 v[26:27], v[228:229], v[68:69], v[26:27] op_sel_hi:[1,0,1]
	v_pk_fma_f32 v[24:25], v[226:227], v[68:69], v[24:25] op_sel_hi:[1,0,1]
	v_pk_fma_f32 v[28:29], v[228:229], v[68:69], v[28:29] op_sel:[0,1,0]
	v_pk_fma_f32 v[4:5], v[226:227], v[68:69], v[4:5] op_sel:[0,1,0]
	v_pk_fma_f32 v[6:7], v[228:229], v[70:71], v[6:7] op_sel_hi:[1,0,1]
	v_pk_fma_f32 v[30:31], v[226:227], v[70:71], v[30:31] op_sel_hi:[1,0,1]
	v_pk_fma_f32 v[20:21], v[228:229], v[72:73], v[20:21] op_sel_hi:[1,0,1]
	v_pk_fma_f32 v[22:23], v[226:227], v[72:73], v[22:23] op_sel_hi:[1,0,1]
	v_pk_fma_f32 v[16:17], v[228:229], v[72:73], v[16:17] op_sel:[0,1,0]
	v_pk_fma_f32 v[0:1], v[226:227], v[72:73], v[0:1] op_sel:[0,1,0]
	v_pk_fma_f32 v[2:3], v[228:229], v[74:75], v[2:3] op_sel_hi:[1,0,1]
	v_pk_fma_f32 v[14:15], v[226:227], v[74:75], v[14:15] op_sel_hi:[1,0,1]
	v_pk_fma_f32 v[18:19], v[228:229], v[92:93], v[18:19] op_sel_hi:[1,0,1]
	v_pk_fma_f32 v[12:13], v[226:227], v[92:93], v[12:13] op_sel_hi:[1,0,1]
	v_pk_fma_f32 v[8:9], v[228:229], v[94:95], v[8:9] op_sel_hi:[1,0,1]
	v_pk_fma_f32 v[10:11], v[226:227], v[94:95], v[10:11] op_sel_hi:[1,0,1]
	s_waitcnt vmcnt(12)
	v_pk_fma_f32 v[40:41], v[232:233], v[76:77], v[26:27] op_sel_hi:[1,0,1]
	v_pk_fma_f32 v[38:39], v[230:231], v[76:77], v[24:25] op_sel_hi:[1,0,1]
	v_pk_fma_f32 v[32:33], v[232:233], v[76:77], v[28:29] op_sel:[0,1,0]
	v_pk_fma_f32 v[34:35], v[230:231], v[76:77], v[4:5] op_sel:[0,1,0]
	v_pk_fma_f32 v[28:29], v[232:233], v[78:79], v[6:7] op_sel_hi:[1,0,1]
	v_pk_fma_f32 v[30:31], v[230:231], v[78:79], v[30:31] op_sel_hi:[1,0,1]
	v_pk_fma_f32 v[24:25], v[232:233], v[96:97], v[18:19] op_sel_hi:[1,0,1]
	v_pk_fma_f32 v[26:27], v[230:231], v[96:97], v[12:13] op_sel_hi:[1,0,1]
	v_pk_fma_f32 v[20:21], v[232:233], v[80:81], v[20:21] op_sel_hi:[1,0,1]
	v_pk_fma_f32 v[22:23], v[230:231], v[80:81], v[22:23] op_sel_hi:[1,0,1]
	v_pk_fma_f32 v[16:17], v[232:233], v[80:81], v[16:17] op_sel:[0,1,0]
	v_pk_fma_f32 v[18:19], v[230:231], v[80:81], v[0:1] op_sel:[0,1,0]
	v_pk_fma_f32 v[12:13], v[232:233], v[82:83], v[2:3] op_sel_hi:[1,0,1]
	v_pk_fma_f32 v[14:15], v[230:231], v[82:83], v[14:15] op_sel_hi:[1,0,1]
	v_pk_fma_f32 v[8:9], v[232:233], v[98:99], v[8:9] op_sel_hi:[1,0,1]
	v_pk_fma_f32 v[10:11], v[230:231], v[98:99], v[10:11] op_sel_hi:[1,0,1]
	v_lshl_add_u64 v[234:235], v[36:37], 0, s[28:29]
	v_add_co_u32_e32 v236, vcc, s3, v234
	s_nop 1
	v_addc_co_u32_e32 v237, vcc, 0, v235, vcc
	v_add_co_u32_e32 v238, vcc, s30, v234
	s_nop 1
	v_addc_co_u32_e32 v239, vcc, 0, v235, vcc
	v_add_co_u32_e32 v240, vcc, s31, v234
	s_nop 1
	v_addc_co_u32_e32 v241, vcc, 0, v235, vcc
	global_load_dwordx4 v[218:221], v[234:235], off
	global_load_dwordx4 v[222:225], v[236:237], off
	global_load_dwordx4 v[226:229], v[238:239], off
	global_load_dwordx4 v[230:233], v[240:241], off
	s_add_u32 s28, s28, 0xc0000
	s_sub_u32 s99, s28, 0xc00000
	s_cmp_ge_u32 s28, 0xc00000
	s_cselect_b32 s28, s99, s28
	s_add_i32 s98, s98, 1
	s_cmp_eq_u32 s98, 4
	s_cbranch_scc0 .Lgemv_loop
	s_waitcnt vmcnt(0)
	v_mbcnt_lo_u32_b32 v0, -1, 0
	v_mbcnt_hi_u32_b32 v0, -1, v0
	v_and_b32_e32 v2, 64, v0
	v_xor_b32_e32 v1, 16, v0
	v_add_u32_e32 v2, 64, v2
	v_cmp_lt_i32_e32 vcc, v1, v2
	s_lshl_b32 s3, s85, 11
	s_add_i32 s3, s3, 0
	v_cndmask_b32_e32 v1, v0, v1, vcc
	v_lshlrev_b32_e32 v37, 2, v1
	v_xor_b32_e32 v1, 32, v0
	v_cmp_lt_i32_e32 vcc, v1, v2
	ds_bpermute_b32 v4, v37, v40
	ds_bpermute_b32 v5, v37, v41
	v_cndmask_b32_e32 v0, v0, v1, vcc
	v_lshlrev_b32_e32 v36, 2, v0
	ds_bpermute_b32 v0, v37, v38
	ds_bpermute_b32 v1, v37, v39
	s_waitcnt lgkmcnt(2)
	v_pk_add_f32 v[4:5], v[40:41], v[4:5]
	ds_bpermute_b32 v6, v36, v4
	ds_bpermute_b32 v7, v36, v5
	s_add_i32 s3, s3, 0x10000
	s_waitcnt lgkmcnt(2)
	v_pk_add_f32 v[0:1], v[38:39], v[0:1]
	ds_bpermute_b32 v2, v36, v0
	ds_bpermute_b32 v3, v36, v1
	v_lshlrev_b32_e32 v38, 4, v168
	v_and_b32_e32 v38, 0xf0, v38
	v_cmp_gt_u32_e32 vcc, 16, v128
	v_add_u32_e32 v38, s3, v38
	s_and_saveexec_b64 s[28:29], vcc
	s_cbranch_execz .LBB0_25
	s_waitcnt lgkmcnt(2)
	v_pk_add_f32 v[4:5], v[4:5], v[6:7]
	s_waitcnt lgkmcnt(0)
	v_pk_add_f32 v[2:3], v[0:1], v[2:3]
	ds_write_b128 v38, v[2:5]

; #define SC_LOAD(tc) do { const size_t o_ = base + (size_t)(tc) * 1024 + q * 4; ld_dec = *(const f32x4*)(DEC + o_); ld_kk = *(const u32x2*)(KKn + o_); ld_bb = *(const u32x2*)(BB + o_); \
;             ld_kp = *(const u32x2*)(KP + o_); ld_rr = *(const u32x2*)(RR + o_); ld_vv = *(const unsigned*)(VV + base + (size_t)(tc) * 1024 + half * 32 + q * 2); } while (0)
; __global__ void __launch_bounds__(NT, 2) mk_fwd(Args args) {
;     ...
;         for (int task_ = bx; task_ < 256 * RMUL(4); task_ += G) {
;             const int tb_ = task_ & 255; const int task = ((tb_ >> 4) << 4) | ((tb_ & 7) << 1) | ((tb_ >> 3) & 1); const int bh = task >> 1, half = task & 1, b = bh >> 4, h = bh & 15;
;             const int stp = tid >> 4, q = tid & 15;
;             const size_t base = ((size_t)b * SEQ + stp) * 1024 + h * 64;
;             f32x4 ld_dec; u32x2 ld_kk, ld_bb, ld_kp, ld_rr; unsigned ld_vv;
;     ...
;             __syncthreads();
;             SC_LOAD(0); SC_STORE();
;             __syncthreads();
;             f32x4 S = (f32x4){0.f, 0.f, 0.f, 0.f};
;             const int row = wave * 4 + (lane >> 4), kl = lane & 15;
.Lp4_task:
	s_and_b32 s3, s48, 0xf0
	s_and_b32 s6, s48, 7
	s_lshl_b32 s6, s6, 1
	s_or_b32 s3, s3, s6
	s_bfe_u32 s6, s48, 0x10003
	s_or_b32 s3, s3, s6
	s_and_b32 s33, s3, 1
	s_lshr_b32 s6, s3, 1
	s_and_b32 s7, s6, 15
	s_lshr_b32 s6, s6, 4
	s_lshl_b32 s6, s6, 21
	s_lshl_b32 s7, s7, 6
	s_or_b32 s6, s6, s7
	s_lshl_b32 s7, s6, 1
	s_lshl_b32 s8, s6, 2
	s_add_u32 s38, s90, s8
	s_addc_u32 s39, s91, 0
	s_add_u32 s40, s30, s7
	s_addc_u32 s41, s31, 0
	s_add_u32 s42, s34, s7
	s_addc_u32 s43, s35, 0
	s_add_u32 s44, s96, s7
	s_addc_u32 s45, s97, 0
	s_add_u32 s46, s28, s7
	s_addc_u32 s47, s29, 0
	s_lshl_b32 s9, s33, 6
	s_add_u32 s9, s9, s7
	s_add_u32 s52, s24, s9
	s_addc_u32 s53, s25, 0
	s_lshl_b32 s9, s33, 7
	s_add_u32 s9, s9, s8
	s_add_u32 s54, s20, s9
	s_addc_u32 s55, s21, 0
	s_waitcnt vmcnt(0) lgkmcnt(0)
	s_barrier
	s_cmp_gt_u32 s85, 3
	s_cbranch_scc1 .Lp4_helper
	v_and_b32_e32 v54, 15, v128
	v_lshrrev_b32_e32 v55, 4, v128
	v_lshl_or_b32 v55, s85, 2, v55
	v_lshlrev_b32_e32 v80, 4, v54
	v_lshlrev_b32_e32 v81, 3, v55
	v_add_u32_e32 v81, 0x5000, v81
	v_mul_u32_u24_e32 v82, 0x90, v55
	v_lshl_add_u32 v82, v54, 3, v82
	v_add_u32_e32 v82, 0xb000, v82
	v_mov_b32_e32 v72, 0
	v_mov_b32_e32 v73, 0
	v_mov_b32_e32 v74, 0
	v_mov_b32_e32 v75, 0
	v_mov_b32_e32 v76, 0
	v_mov_b32_e32 v77, 0
	v_mov_b32_e32 v78, 0
	v_mov_b32_e32 v79, 0
	s_movk_i32 s10, 0x80
	s_barrier
	s_nop 0
	s_nop 0
	s_nop 0
	s_nop 0
	s_nop 0
	s_nop 0
